# sample row phase: gate/gain and shift/scale fragment loads of all column blocks requested up front (no load-after-store waits)
# baseline (speedup 1.0000x reference)
.LBB0_899:
	v_lshrrev_b32_e32 v3, 3, v54
	v_lshlrev_b32_e32 v196, 2, v32
	v_ashrrev_i32_e32 v2, 11, v62
	v_add_u32_e32 v3, 8, v3
	v_lshl_add_u64 v[0:1], v[0:1], 0, v[196:197]
	v_lshl_add_u64 v[16:17], v[34:35], 0, v[66:67]
	v_cndmask_b32_e64 v55, v3, v2, s[40:41]
	global_load_dwordx4 v[12:15], v[0:1], off offset:3072 nt
	global_load_dwordx4 v[8:11], v[0:1], off offset:2048 nt
	global_load_dwordx4 v[4:7], v[0:1], off offset:1024 nt
	s_nop 0
	global_load_dwordx4 v[0:3], v[0:1], off nt
	s_nop 0
	global_load_dwordx4 v[28:31], v[16:17], off nt
	global_load_dwordx4 v[24:27], v[16:17], off offset:1024 nt
	s_mov_b32 s0, 0xc000
	v_mov_b32_e32 v61, v197
	s_waitcnt vmcnt(1)
	v_mov_b32_e32 v20, v29
	s_waitcnt vmcnt(0)
	v_mov_b32_e32 v21, v25
	v_mov_b32_e32 v18, v28
	v_mov_b32_e32 v19, v24
	v_pk_mul_f32 v[20:21], v[20:21], v[20:21]
	s_nop 0
	v_pk_fma_f32 v[18:19], v[18:19], v[18:19], v[20:21]
	v_mov_b32_e32 v20, v30
	v_mov_b32_e32 v21, v26
	v_pk_fma_f32 v[18:19], v[20:21], v[20:21], v[18:19]
	v_mov_b32_e32 v20, v31
	v_mov_b32_e32 v21, v27
	v_pk_fma_f32 v[64:65], v[20:21], v[20:21], v[18:19]
	global_load_dwordx4 v[20:23], v[16:17], off offset:2048 nt
	s_nop 0
	global_load_dwordx4 v[16:19], v[16:17], off offset:3072 nt
	v_add_f32_e32 v57, v64, v65
	s_waitcnt vmcnt(1)
	v_mov_b32_e32 v70, v21
	s_waitcnt vmcnt(0)
	v_mov_b32_e32 v71, v17
	v_mov_b32_e32 v68, v20
	v_mov_b32_e32 v69, v16
	v_pk_mul_f32 v[70:71], v[70:71], v[70:71]
	s_nop 0
	v_pk_fma_f32 v[68:69], v[68:69], v[68:69], v[70:71]
	v_mov_b32_e32 v70, v22
	v_mov_b32_e32 v71, v18
	v_pk_fma_f32 v[68:69], v[70:71], v[70:71], v[68:69]
	v_mov_b32_e32 v70, v23
	v_mov_b32_e32 v71, v19
	v_pk_fma_f32 v[68:69], v[70:71], v[70:71], v[68:69]
	s_nop 0
	v_add_f32_e32 v57, v57, v68
	v_add_f32_e32 v57, v57, v69
	v_mov_b64_e32 v[68:69], s[12:13]
	v_mad_i64_i32 v[68:69], s[0:1], v55, s0, v[68:69]
	s_mov_b64 s[0:1], 0x2000
	s_nop 0
	v_lshl_add_u64 v[68:69], v[68:69], 0, s[0:1]
	v_lshl_add_u64 v[70:71], v[68:69], 0, v[196:197]
	global_load_dwordx4 v[70:73], v[70:71], off
	s_nop 0
	global_load_dwordx4 v[74:77], v[40:41], off
	v_mov_b32_e32 v121, v197
	v_mov_b32_e32 v120, v56
	v_lshl_add_u64 v[122:123], v[68:69], 0, v[120:121]
	global_load_dwordx4 v[124:127], v[122:123], off
	global_load_dwordx4 v[128:131], v[40:41], off offset:1024
	v_mov_b32_e32 v120, v58
	v_lshl_add_u64 v[122:123], v[68:69], 0, v[120:121]
	global_load_dwordx4 v[132:135], v[122:123], off
	global_load_dwordx4 v[136:139], v[40:41], off offset:2048
	v_mov_b32_e32 v120, v60
	v_lshl_add_u64 v[122:123], v[68:69], 0, v[120:121]
	global_load_dwordx4 v[140:143], v[122:123], off
	global_load_dwordx4 v[144:147], v[40:41], off offset:3072
	ds_bpermute_b32 v59, v33, v57
	s_waitcnt lgkmcnt(0)
	v_add_f32_e32 v57, v57, v59
	ds_bpermute_b32 v59, v37, v57
	s_waitcnt lgkmcnt(0)
	v_add_f32_e32 v57, v57, v59
	ds_bpermute_b32 v59, v45, v57
	s_waitcnt lgkmcnt(0)
	v_add_f32_e32 v57, v57, v59
	ds_bpermute_b32 v59, v47, v57
	s_waitcnt lgkmcnt(0)
	v_add_f32_e32 v57, v57, v59
	ds_bpermute_b32 v59, v49, v57
	s_waitcnt lgkmcnt(0)
	v_add_f32_e32 v57, v57, v59
	ds_bpermute_b32 v59, v51, v57
	s_waitcnt lgkmcnt(0)
	v_add_f32_e32 v57, v57, v59
	v_fmamk_f32 v57, v57, 0x3a800000, v227
	v_cmp_gt_f32_e32 vcc, s15, v57
	v_mul_f32_e32 v59, 0x4b800000, v57
	s_nop 0
	v_cndmask_b32_e32 v57, v57, v59, vcc
	v_rsq_f32_e32 v57, v57
	s_nop 0
	v_mul_f32_e32 v59, 0x45800000, v57
	v_cndmask_b32_e32 v64, v57, v59, vcc
	v_pk_mul_f32 v[30:31], v[30:31], v[64:65] op_sel_hi:[1,0]
	v_pk_mul_f32 v[28:29], v[28:29], v[64:65] op_sel_hi:[1,0]
	v_mov_b32_e32 v57, v197
	v_pk_mul_f32 v[24:25], v[24:25], v[64:65] op_sel_hi:[1,0]
	v_pk_mul_f32 v[26:27], v[26:27], v[64:65] op_sel_hi:[1,0]
	v_mov_b32_e32 v59, v197
	v_pk_mul_f32 v[20:21], v[20:21], v[64:65] op_sel_hi:[1,0]
	v_pk_mul_f32 v[22:23], v[22:23], v[64:65] op_sel_hi:[1,0]
	v_pk_mul_f32 v[16:17], v[16:17], v[64:65] op_sel_hi:[1,0]
	v_pk_mul_f32 v[18:19], v[18:19], v[64:65] op_sel_hi:[1,0]
	s_andn2_b64 vcc, exec, s[34:35]
	s_waitcnt vmcnt(6)
	v_pk_mul_f32 v[28:29], v[74:75], v[28:29]
	v_pk_mul_f32 v[30:31], v[76:77], v[30:31]
	v_pk_fma_f32 v[0:1], v[70:71], v[28:29], v[0:1]
	v_pk_fma_f32 v[2:3], v[72:73], v[30:31], v[2:3]
	v_lshl_add_u64 v[28:29], v[52:53], 0, v[66:67]
	global_store_dwordx4 v[28:29], v[0:3], off
	v_lshl_add_u64 v[30:31], v[68:69], 0, v[56:57]
	s_waitcnt vmcnt(1)
	v_pk_mul_f32 v[26:27], v[130:131], v[26:27]
	v_pk_mul_f32 v[24:25], v[128:129], v[24:25]
	v_pk_fma_f32 v[6:7], v[126:127], v[26:27], v[6:7]
	v_pk_fma_f32 v[4:5], v[124:125], v[24:25], v[4:5]
	global_store_dwordx4 v[28:29], v[4:7], off offset:1024
	v_lshl_add_u64 v[24:25], v[68:69], 0, v[58:59]
	s_nop 0
	s_waitcnt vmcnt(2)
	v_pk_mul_f32 v[22:23], v[138:139], v[22:23]
	v_pk_mul_f32 v[20:21], v[136:137], v[20:21]
	v_pk_fma_f32 v[10:11], v[134:135], v[22:23], v[10:11]
	v_pk_fma_f32 v[8:9], v[132:133], v[20:21], v[8:9]
	global_store_dwordx4 v[28:29], v[8:11], off offset:2048
	v_lshl_add_u64 v[20:21], v[68:69], 0, v[60:61]
	s_nop 0
	s_waitcnt vmcnt(3)
	v_pk_mul_f32 v[18:19], v[146:147], v[18:19]
	v_pk_mul_f32 v[16:17], v[144:145], v[16:17]
	v_pk_fma_f32 v[14:15], v[142:143], v[18:19], v[14:15]
	v_pk_fma_f32 v[12:13], v[140:141], v[16:17], v[12:13]
	global_store_dwordx4 v[28:29], v[12:15], off offset:3072
	s_cbranch_vccnz .LBB0_890
	v_mov_b32_e32 v20, v1
	v_mov_b32_e32 v21, v5
	v_mov_b32_e32 v18, v0
	v_mov_b32_e32 v19, v4
	v_pk_mul_f32 v[20:21], v[20:21], v[20:21]
	v_mov_b32_e32 v22, v13
	v_pk_fma_f32 v[18:19], v[18:19], v[18:19], v[20:21]
	v_mov_b32_e32 v20, v2
	v_mov_b32_e32 v21, v6
	v_pk_fma_f32 v[18:19], v[20:21], v[20:21], v[18:19]
	v_mov_b32_e32 v20, v3
	v_mov_b32_e32 v21, v7
	v_mov_b32_e32 v23, v9
	v_pk_fma_f32 v[18:19], v[20:21], v[20:21], v[18:19]
	v_mov_b32_e32 v20, v12
	v_mov_b32_e32 v21, v8
	v_pk_mul_f32 v[22:23], v[22:23], v[22:23]
	v_add_f32_e32 v18, v18, v19
	v_pk_fma_f32 v[20:21], v[20:21], v[20:21], v[22:23]
	v_mov_b32_e32 v22, v14
	v_mov_b32_e32 v23, v10
	v_pk_fma_f32 v[20:21], v[22:23], v[22:23], v[20:21]
	v_mov_b32_e32 v22, v15
	v_mov_b32_e32 v23, v11
	v_pk_fma_f32 v[20:21], v[22:23], v[22:23], v[20:21]
	s_mov_b32 s0, 0xc000
	v_add_f32_e32 v18, v21, v18
	v_add_f32_e32 v18, v20, v18
	ds_bpermute_b32 v19, v33, v18
	v_mad_i64_i32 v[16:17], s[0:1], v55, s0, 0
	v_lshl_add_u64 v[16:17], s[36:37], 0, v[16:17]
	s_mov_b64 s[0:1], 0x1000
	s_waitcnt lgkmcnt(0)
	v_add_f32_e32 v18, v18, v19
	ds_bpermute_b32 v19, v37, v18
	v_lshl_add_u64 v[28:29], v[16:17], 0, s[0:1]
	v_lshl_add_u64 v[30:31], v[16:17], 0, v[196:197]
	v_lshl_add_u64 v[20:21], v[28:29], 0, v[196:197]
	s_waitcnt lgkmcnt(0)
	v_add_f32_e32 v18, v18, v19
	ds_bpermute_b32 v19, v45, v18
	s_waitcnt lgkmcnt(0)
	v_add_f32_e32 v18, v18, v19
	ds_bpermute_b32 v19, v47, v18
	s_waitcnt lgkmcnt(0)
	v_add_f32_e32 v18, v18, v19
	ds_bpermute_b32 v19, v49, v18
	s_waitcnt lgkmcnt(0)
	v_add_f32_e32 v18, v18, v19
	ds_bpermute_b32 v19, v51, v18
	s_waitcnt lgkmcnt(0)
	v_add_f32_e32 v18, v18, v19
	v_fmamk_f32 v18, v18, 0x3a800000, v227
	v_cmp_gt_f32_e32 vcc, s15, v18
	v_mul_f32_e32 v19, 0x4b800000, v18
	s_nop 0
	v_cndmask_b32_e32 v18, v18, v19, vcc
	v_rsq_f32_e32 v18, v18
	s_nop 0
	v_mul_f32_e32 v19, 0x45800000, v18
	v_cndmask_b32_e32 v24, v18, v19, vcc
	v_lshlrev_b32_e32 v18, 1, v54
	v_and_b32_e32 v55, 0xffffffe0, v18
	v_and_or_b32 v18, v54, 15, v36
	v_lshlrev_b32_e32 v18, 4, v18
	v_mov_b32_e32 v19, v197
	v_lshl_add_u64 v[26:27], v[38:39], 0, v[18:19]
	global_load_dwordx4 v[16:19], v[30:31], off
	s_nop 0
	global_load_dwordx4 v[20:23], v[20:21], off
	s_nop 0
	global_load_dwordx4 v[64:67], v[42:43], off
	v_mov_b32_e32 v121, v197
	global_load_dwordx4 v[148:151], v[42:43], off offset:1024
	v_mov_b32_e32 v120, v56
	v_lshl_add_u64 v[122:123], v[28:29], 0, v[120:121]
	global_load_dwordx4 v[152:155], v[122:123], off
	global_load_dwordx4 v[156:159], v[30:31], off offset:1024
	global_load_dwordx4 v[160:163], v[30:31], off offset:2048
	v_mov_b32_e32 v120, v58
	v_lshl_add_u64 v[122:123], v[28:29], 0, v[120:121]
	global_load_dwordx4 v[164:167], v[122:123], off
	global_load_dwordx4 v[168:171], v[42:43], off offset:2048
	global_load_dwordx4 v[172:175], v[42:43], off offset:3072
	v_mov_b32_e32 v120, v60
	v_lshl_add_u64 v[122:123], v[28:29], 0, v[120:121]
	global_load_dwordx4 v[176:179], v[122:123], off
	global_load_dwordx4 v[180:183], v[30:31], off offset:3072
	v_pk_mul_f32 v[2:3], v[2:3], v[24:25] op_sel_hi:[1,0]
	v_pk_mul_f32 v[0:1], v[0:1], v[24:25] op_sel_hi:[1,0]
	s_waitcnt vmcnt(10)
	v_pk_add_f32 v[22:23], v[22:23], 1.0 op_sel_hi:[1,0]
	s_waitcnt vmcnt(9)
	v_pk_mul_f32 v[0:1], v[64:65], v[0:1]
	v_pk_mul_f32 v[2:3], v[66:67], v[2:3]
	v_pk_add_f32 v[20:21], v[20:21], 1.0 op_sel_hi:[1,0]
	v_pk_fma_f32 v[18:19], v[22:23], v[2:3], v[18:19]
	v_pk_fma_f32 v[0:1], v[20:21], v[0:1], v[16:17]
	s_nop 0
	v_cvt_pk_bf16_f32 v2, v0, v1
	v_cvt_pk_bf16_f32 v3, v18, v19
	s_and_saveexec_b64 s[0:1], s[38:39]
	s_xor_b64 s[0:1], exec, s[0:1]
	s_cbranch_execz .LBB0_902
	v_or_b32_e32 v196, v55, v44
	v_lshlrev_b64 v[0:1], 10, v[196:197]
	v_lshl_add_u64 v[0:1], v[26:27], 0, v[0:1]
	global_store_dwordx2 v[0:1], v[2:3], off

.LBB0_904:
	s_or_b64 exec, exec, s[0:1]
	v_mov_b32_e32 v57, v197
	v_lshl_add_u64 v[2:3], v[28:29], 0, v[56:57]
	v_mov_b32_e32 v25, v24
	v_mov_b32_e32 v2, v24
	v_mov_b32_e32 v3, v24
	v_pk_mul_f32 v[2:3], v[6:7], v[2:3]
	v_pk_mul_f32 v[4:5], v[4:5], v[24:25]
	s_waitcnt vmcnt(1)
	v_pk_mul_f32 v[2:3], v[2:3], v[150:151]
	v_pk_mul_f32 v[4:5], v[4:5], v[148:149]
	v_pk_add_f32 v[6:7], v[154:155], 1.0 op_sel_hi:[1,0]
	v_pk_add_f32 v[16:17], v[152:153], 1.0 op_sel_hi:[1,0]
	v_pk_fma_f32 v[6:7], v[6:7], v[2:3], v[158:159]
	v_pk_fma_f32 v[2:3], v[16:17], v[4:5], v[156:157]
	s_nop 0
	v_cvt_pk_bf16_f32 v2, v2, v3
	v_cvt_pk_bf16_f32 v3, v6, v7
	s_and_saveexec_b64 s[0:1], s[38:39]
	s_xor_b64 s[0:1], exec, s[0:1]
	s_cbranch_execz .LBB0_906
	v_or_b32_e32 v4, v55, v46
	v_mov_b32_e32 v5, v197
	v_lshlrev_b64 v[4:5], 10, v[4:5]
	v_lshl_add_u64 v[4:5], v[26:27], 0, v[4:5]
	global_store_dwordx2 v[4:5], v[2:3], off

.LBB0_908:
	s_or_b64 exec, exec, s[0:1]
	v_mov_b32_e32 v59, v197
	v_lshl_add_u64 v[6:7], v[28:29], 0, v[58:59]
	v_mov_b32_e32 v6, v24
	v_mov_b32_e32 v7, v24
	v_pk_mul_f32 v[8:9], v[8:9], v[24:25]
	v_pk_mul_f32 v[6:7], v[10:11], v[6:7]
	s_waitcnt vmcnt(2)
	v_pk_add_f32 v[16:17], v[164:165], 1.0 op_sel_hi:[1,0]
	v_pk_mul_f32 v[8:9], v[8:9], v[168:169]
	v_pk_mul_f32 v[6:7], v[6:7], v[170:171]
	v_pk_add_f32 v[10:11], v[166:167], 1.0 op_sel_hi:[1,0]
	v_pk_fma_f32 v[2:3], v[16:17], v[8:9], v[160:161]
	v_pk_fma_f32 v[4:5], v[10:11], v[6:7], v[162:163]
	v_cvt_pk_bf16_f32 v2, v2, v3
	s_nop 0
	v_cvt_pk_bf16_f32 v3, v4, v5
	s_and_saveexec_b64 s[0:1], s[38:39]
	s_xor_b64 s[0:1], exec, s[0:1]
	s_cbranch_execz .LBB0_910
	v_or_b32_e32 v4, v55, v48
	v_mov_b32_e32 v5, v197
	v_lshlrev_b64 v[4:5], 10, v[4:5]
	v_lshl_add_u64 v[4:5], v[26:27], 0, v[4:5]
	global_store_dwordx2 v[4:5], v[2:3], off

.LBB0_912:
	s_or_b64 exec, exec, s[0:1]
	v_mov_b32_e32 v61, v197
	v_lshl_add_u64 v[6:7], v[28:29], 0, v[60:61]
	s_nop 0
	v_mov_b32_e32 v10, v24
	v_mov_b32_e32 v11, v24
	v_pk_mul_f32 v[12:13], v[12:13], v[24:25]
	v_pk_mul_f32 v[10:11], v[14:15], v[10:11]
	s_waitcnt vmcnt(3)
	v_pk_mul_f32 v[2:3], v[12:13], v[172:173]
	v_pk_add_f32 v[6:7], v[176:177], 1.0 op_sel_hi:[1,0]
	v_pk_mul_f32 v[4:5], v[10:11], v[174:175]
	v_pk_add_f32 v[8:9], v[178:179], 1.0 op_sel_hi:[1,0]
	v_pk_fma_f32 v[2:3], v[6:7], v[2:3], v[180:181]
	v_pk_fma_f32 v[4:5], v[8:9], v[4:5], v[182:183]
	v_cvt_pk_bf16_f32 v2, v2, v3
	s_nop 0
	v_cvt_pk_bf16_f32 v3, v4, v5
	s_and_saveexec_b64 s[0:1], s[38:39]
	s_xor_b64 s[0:1], exec, s[0:1]
	s_cbranch_execz .LBB0_914
	v_or_b32_e32 v196, v55, v50
	v_lshlrev_b64 v[0:1], 10, v[196:197]
	v_lshl_add_u64 v[0:1], v[26:27], 0, v[0:1]
	global_store_dwordx2 v[0:1], v[2:3], off
